# attention tile loop: removed dead zero-init of block-B score accumulator (23 instr/tile) and shrank the 24-state MFMA->VALU pad to 4 (path already has >=19 states)
# speedup vs baseline: 1.0170x; 1.0014x over previous
; #define LAS __attribute__((address_space(3)))
; __device__ __forceinline__ void attn_item2(const bf16* QpA, const bf16* QpB, bf16* OpA, bf16* OpB, int ldq, const AttnSeg& s0, const AttnSeg& s1, int relB_minus_relA, bool two, const LAS float* tbl, LAS unsigned char* ring, int lane) {
;     ...
;         LAS unsigned char* slot = ring + (t & 1) * 8192;
;         if (t + 1 < nt) asm volatile("s_waitcnt vmcnt(8)" ::: "memory"); else asm volatile("s_waitcnt vmcnt(0)" ::: "memory");
;         bf16x8 kf[4], vf[4];
; #pragma unroll
;         for (int d0 = 0; d0 < 4; ++d0) kf[d0] = *(const LAS bf16x8*)(slot + keyl * 128 + (((2 * d0 + hi) ^ kx) * 16));
; #pragma unroll
;         for (int kh = 0; kh < 2; ++kh)
; #pragma unroll
;             for (int dh = 0; dh < 2; ++dh) vf[kh * 2 + dh] = *(const LAS bf16x8*)(slot + 4096 + dh * 2048 + ql * 64 + (((kh * 2 + hi) ^ vx) * 16));
;         asm volatile("s_waitcnt lgkmcnt(4)" : "+v"(kf[0]), "+v"(kf[1]), "+v"(kf[2]), "+v"(kf[3]) :: "memory");
;         f32x16 sa = f32x16{}, sb = f32x16{};
; #pragma unroll
;         for (int d0 = 0; d0 < 4; ++d0) { sa = __builtin_amdgcn_mfma_f32_32x32x16_bf16(kf[d0], qa[d0], sa, 0, 0, 0); if (two) sb = __builtin_amdgcn_mfma_f32_32x32x16_bf16(kf[d0], qb_[d0], sb, 0, 0, 0); }
.LBB0_706:
	s_and_b32 s6, s5, 0x2000
	s_add_i32 s55, s60, s6
	v_add_u32_e32 v66, s55, v215
	v_add_u32_e32 v67, v66, v217
	v_add_u32_e32 v68, v66, v218
	v_add_u32_e32 v69, v66, v219
	v_add_u32_e32 v66, v66, v220
	v_add_u32_e32 v70, s55, v216
	v_add_u32_e32 v71, v70, v221
	ds_read_b128 v[82:85], v66 offset:16384
	ds_read_b128 v[86:89], v69 offset:16384
	ds_read_b128 v[90:93], v68 offset:16384
	ds_read_b128 v[94:97], v67 offset:16384
	ds_read_b128 v[158:161], v71 offset:20480
	ds_read_b128 v[150:153], v71 offset:22528
	v_add_u32_e32 v66, v70, v222
	v_cndmask_b32_e64 v98, 0, 1, s[8:9]
	ds_read_b128 v[154:157], v66 offset:20480
	ds_read_b128 v[146:149], v66 offset:22528
	s_waitcnt lgkmcnt(0)
	s_waitcnt lgkmcnt(4)
	v_cmp_ne_u32_e64 s[6:7], 1, v98
	v_mfma_f32_32x32x16_bf16 v[98:113], v[94:97], v[142:145], 0
	s_andn2_b64 vcc, exec, s[8:9]
	s_cbranch_vccnz .LBB0_708
	v_mfma_f32_32x32x16_bf16 v[66:81], v[94:97], v[134:137], 0

; __device__ __forceinline__ void attn_item2(const bf16* QpA, const bf16* QpB, bf16* OpA, bf16* OpB, int ldq, const AttnSeg& s0, const AttnSeg& s1, int relB_minus_relA, bool two, const LAS float* tbl, LAS unsigned char* ring, int lane) {
;     ...
;         asm volatile("s_nop 15\n\ts_nop 7" : "+v"(sa), "+v"(sb));
;         const int relA = (t < nt0) ? (s0.rel0 + t * 32) : (s1.rel0 + (t - nt0) * 32);
.LBB0_720:
	s_cmp_lt_i32 s54, s31
	s_cselect_b32 s52, 0, s31
	s_cselect_b32 s53, s20, 0
	s_lshl_b32 s52, s52, 5
	s_sub_i32 s69, s53, s52
	s_add_i32 s70, s86, s69
	s_cmpk_gt_i32 s70, 0xff61
	s_cselect_b64 s[52:53], -1, 0
	s_mov_b64 s[54:55], -1
	s_and_b64 vcc, exec, s[52:53]
	s_nop 3
	s_cbranch_vccz .LBB0_722
	v_lshl_add_u32 v96, s70, 2, v189
	ds_read2_b32 v[82:83], v96 offset0:192 offset1:193
	ds_read2_b32 v[84:85], v96 offset0:194 offset1:195
	ds_read2_b32 v[86:87], v96 offset0:196 offset1:197
	ds_read2_b32 v[88:89], v96 offset0:198 offset1:199
	ds_read2_b32 v[90:91], v96 offset0:208 offset1:209
	s_waitcnt lgkmcnt(0)
	v_fma_f32 v82, v98, v224, v82
	v_fma_f32 v83, v99, v224, v83
	v_fma_f32 v84, v100, v224, v84
	v_fma_f32 v85, v101, v224, v85
	v_fma_f32 v86, v102, v224, v86
	v_fma_f32 v87, v103, v224, v87
	s_nop 0
	v_max_f32_e32 v228, v82, v82
	v_max_f32_e32 v227, v83, v83
	v_max_f32_e32 v227, v228, v227
	v_max3_f32 v227, v227, v84, v85
	ds_read2_b32 v[92:93], v96 offset0:210 offset1:211
	ds_read2_b32 v[94:95], v96 offset0:212 offset1:213
	ds_read2_b32 v[96:97], v96 offset0:214 offset1:215
	v_max3_f32 v227, v227, v86, v87
	v_fma_f32 v88, v104, v224, v88
	v_fma_f32 v89, v105, v224, v89
	v_fma_f32 v90, v106, v224, v90
	v_fma_f32 v91, v107, v224, v91
	s_waitcnt lgkmcnt(0)
	v_fma_f32 v92, v108, v224, v92
	v_fma_f32 v93, v109, v224, v93
	v_fma_f32 v94, v110, v224, v94
	v_max3_f32 v227, v227, v88, v89
	v_max3_f32 v227, v227, v90, v91
	v_max3_f32 v227, v227, v92, v93
	v_fma_f32 v95, v111, v224, v95
	v_fma_f32 v96, v112, v224, v96
	v_fma_f32 v97, v113, v224, v97
	s_mov_b64 s[54:55], 0
	v_max3_f32 v227, v227, v94, v95
	v_max3_f32 v227, v227, v96, v97
